# barrier leader path: dropped the per-XCC XGEN release atomic (followers poll TOPGEN since v121), so leaders no longer wait for its ack before starting the next phase
# speedup vs baseline: 1.0270x; 1.0031x over previous
.LBB0_134:
	s_or_b64 exec, exec, s[8:9]
	s_mov_b64 s[8:9], exec
	v_mbcnt_lo_u32_b32 v0, s8, 0
	v_mbcnt_hi_u32_b32 v0, s9, v0
	v_cmp_eq_u32_e32 vcc, 0, v0
	s_waitcnt vmcnt(0)
	s_and_saveexec_b64 s[12:13], vcc
	s_cbranch_execz .LBB0_136
	s_bcnt1_i32_b64 s8, s[8:9]
	v_mov_b32_e32 v0, s8
.LBB0_136:
	s_or_b64 exec, exec, s[12:13]
	s_waitcnt vmcnt(0)

.LBB0_1219:
	s_or_b64 exec, exec, s[2:3]
	s_mov_b64 s[2:3], exec
	v_mbcnt_lo_u32_b32 v0, s2, 0
	v_mbcnt_hi_u32_b32 v0, s3, v0
	v_cmp_eq_u32_e32 vcc, 0, v0
	s_waitcnt vmcnt(0)
	s_and_saveexec_b64 s[8:9], vcc
	s_cbranch_execz .LBB0_1221
	s_bcnt1_i32_b64 s2, s[2:3]
	v_mov_b32_e32 v0, s2
.LBB0_1221:
	s_or_b64 exec, exec, s[8:9]
	s_waitcnt vmcnt(0)
